# plus: fox sample-unit F cumsum loads batched (wave 0), and all later-GEMM weight conversion items moved into the idle workgroups of the input projection's last round (16 items per idle wave instead of
# baseline (speedup 1.0000x reference)
; #define PG8_STAGE(bufoff, gbase, voff) do { _Pragma("unroll") for (int _i = 0; _i < 2; ++_i) \
;         __builtin_amdgcn_global_load_lds((const unsigned*)((const char*)(gbase) + (voff)[_i]), (PG8_LAS unsigned*)(lds + (bufoff) + ldsw + _i * 8192), 16, 0, 0); } while (0)
; template <class Epi, class Sched, bool ALIGN_EPI = false, bool SP2 = false>
; __device__ __forceinline__ void gemm_phase(PG8_LAS unsigned char* lds, const Gemm g, const Sched& S, const Epi& E) {
;     ...
;     Unit cur, nxt; int ui = 0;
;     if (!S.next(0, cur)) return;
;     f32x4 acc[2][2][4][2];
; #pragma unroll
;     for (int a = 0; a < 2; ++a)
; #pragma unroll
;         for (int b = 0; b < 2; ++b)
; #pragma unroll
;             for (int m = 0; m < 4; ++m)
; #pragma unroll
;                 for (int n = 0; n < 2; ++n) acc[a][b][m][n] = (f32x4){0.f, 0.f, 0.f, 0.f};
;     bf16x8 At[4][2], B0[2][2], B1[2][2];
;     const char* cA = (const char*)g.A + (size_t)cur.pm * tstepA + (size_t)cur.k0 * 2; const char* cB = (const char*)g.Bt + (size_t)cur.pn * tstepB + (size_t)cur.k0 * 2;
;     S.a_ready(cur);
;     if constexpr (SP2) {
;         PG8_STAGE(PG8_SB(0, 0), cB, voffB); PG8_STAGE(PG8_SB(0, 1), cB + hstepB, voffB); PG8_STAGE(PG8_SA(0, 0), cA, voffA); PG8_STAGE(PG8_SA(0, 1), cA + hstepA, voffA);
;         if (wr == 1) PG8_BAR;
;         PG8_WAIT_V(2); PG8_BAR;
;         PG8_STAGE(PG8_SB(1, 0), cB + kstep, voffB); PG8_STAGE(PG8_SA(1, 0), cA + kstep, voffA); PG8_STAGE(PG8_SB(1, 1), cB + hstepB + kstep, voffB);
;         PG8_WAIT_V(6); PG8_BAR;
;     } else {
;         PG8_STAGE(PG8_SB(0, 0), cB, voffB); PG8_STAGE(PG8_SA(0, 0), cA, voffA); PG8_STAGE(PG8_SB(0, 1), cB + hstepB, voffB); PG8_STAGE(PG8_SA(0, 1), cA + hstepA, voffA);
;         if (wr == 1) PG8_BAR;
;         PG8_WAIT_V(4); PG8_BAR;
;         PG8_STAGE(PG8_SB(1, 0), cB + kstep, voffB); PG8_STAGE(PG8_SA(1, 0), cA + kstep, voffA); PG8_STAGE(PG8_SB(1, 1), cB + hstepB + kstep, voffB);
;         PG8_WAIT_V(6); PG8_BAR;
; __global__ void __launch_bounds__(512, 2) mega_fwd(Args a) {
;     ...
;   constexpr int CV_I_BD = 16 * 32, CV_I_OUT = 32 * 32, CV_I_UP = 32 * 256, CV_I_DN = 128 * 32, CV_NIT = 2 * CV_I_BD + CV_I_OUT + CV_I_UP + CV_I_DN;
;   const int cv_nwg1 = (MT / 256) * (NIN_PAD / 256), cv_maxu = (cv_nwg1 + G - 1) / G, cv_ni = G * cv_maxu - cv_nwg1;
;   const int CV_NP1 = (cv_ni * 8 * 6 < CV_NIT) ? cv_ni * 8 * 6 : CV_NIT;
.LBB0_91:
.LBB0_92:
	s_cmp_lt_i32 s86, 2
	s_cselect_b64 s[2:3], -1, 0
	s_add_u32 s80, s84, 0x2900000
	s_addc_u32 s81, s85, 0
	v_writelane_b32 v251, s56, 48
	s_add_u32 s4, s84, 0x3100000
	s_addc_u32 s5, s85, 0
	v_writelane_b32 v251, s57, 49
	v_writelane_b32 v251, s4, 50
	s_nop 1
	v_writelane_b32 v251, s5, 51
	s_add_u32 s4, s84, 0x3900000
	s_addc_u32 s5, s85, 0
	v_writelane_b32 v251, s4, 52
	s_nop 1
	v_writelane_b32 v251, s5, 53
	s_add_u32 s4, s84, 0x7900000
	s_addc_u32 s5, s85, 0
	v_writelane_b32 v251, s4, 54
	s_nop 1
	v_writelane_b32 v251, s5, 55
	s_add_u32 s4, s84, 0xdb00000
	s_addc_u32 s5, s85, 0
	s_add_u32 s66, s84, 0x1a100000
	v_writelane_b32 v251, s4, 56
	s_addc_u32 s67, s85, 0
	s_nop 0
	v_writelane_b32 v251, s5, 57
	s_add_u32 s4, s84, 0x22500000
	s_addc_u32 s5, s85, 0
	s_abs_i32 s9, s82
	v_cvt_f32_u32_e32 v2, s9
	s_sub_i32 s7, 0, s9
	v_writelane_b32 v251, s4, 58
	v_rcp_iflag_f32_e32 v2, v2
	s_nop 0
	v_writelane_b32 v251, s5, 59
	s_add_i32 s4, s82, 0xa91
	s_abs_i32 s6, s4
	v_mul_f32_e32 v2, 0x4f7ffffe, v2
	v_cvt_u32_f32_e32 v2, v2
	s_ashr_i32 s5, s4, 31
	v_readfirstlane_b32 s8, v2
	s_mul_i32 s7, s7, s8
	s_mul_hi_u32 s7, s8, s7
	s_add_i32 s7, s8, s7
	v_writelane_b32 v251, s7, 60
	s_mul_hi_u32 s7, s6, s7
	s_mul_i32 s7, s7, s9
	s_sub_i32 s6, s6, s7
	s_sub_i32 s7, s6, s9
	s_cmp_ge_u32 s6, s9
	s_cselect_b32 s6, s7, s6
	s_sub_i32 s7, s6, s9
	s_cmp_ge_u32 s6, s9
	s_cselect_b32 s6, s7, s6
	v_writelane_b32 v251, s9, 61
	s_xor_b32 s6, s6, s5
	s_sub_i32 s5, s5, s6
	v_writelane_b32 v251, s88, 62
	s_add_i32 s5, s4, s5
	s_add_i32 s13, s5, 0xfffff56e
	v_writelane_b32 v250, s90, 0
	v_writelane_b32 v250, s91, 1
	v_writelane_b32 v250, s92, 2
	s_cmpk_lt_i32 s5, 0xb02
	s_mul_i32 s4, s13, 0x80
	v_writelane_b32 v250, s93, 3
	s_cselect_b32 s56, s4, 0x3800
	s_and_b64 s[76:77], s[2:3], s[0:1]
	v_writelane_b32 v250, s94, 4
	s_andn2_b64 vcc, exec, s[76:77]
	v_writelane_b32 v250, s95, 5
	v_writelane_b32 v251, s89, 63
	v_writelane_b32 v250, s68, 6
	s_cbranch_vccnz .LBB0_202
	v_lshlrev_b32_e32 v174, 2, v1
	s_cmpk_gt_i32 s68, 0xa91
	v_readfirstlane_b32 s4, v1
	s_cbranch_scc1 .LBB0_177
	v_lshrrev_b32_e32 v4, 1, v1
	v_lshrrev_b32_e32 v5, 5, v1
	v_and_b32_e32 v4, 24, v4
	v_and_b32_e32 v5, 4, v5
	v_bfe_u32 v6, v1, 2, 2
	v_lshlrev_b32_e32 v2, 4, v1
	v_and_b32_e32 v3, 32, v1
	v_bfe_u32 v175, v1, 2, 4
	v_or3_b32 v4, v5, v6, v4
	v_lshrrev_b32_e32 v5, 3, v1
	s_movk_i32 s0, 0x70
	v_bitop3_b32 v10, v2, v3, 48 bitop3:0x6c
	v_and_b32_e32 v11, 64, v1
	v_and_or_b32 v6, v5, s0, v175
	s_movk_i32 s0, 0x60
	v_add_u32_e32 v12, 0x2000, v2
	v_or_b32_e32 v3, v10, v11
	v_and_or_b32 v5, v5, s0, v4
	v_lshrrev_b32_e32 v2, 7, v12
	s_movk_i32 s0, 0xf0
	v_lshl_or_b32 v148, v5, 12, v3
	v_and_or_b32 v5, v2, s0, v175
	s_movk_i32 s0, 0xe0
	v_and_or_b32 v2, v2, s0, v4
	s_min_i32 s0, s68, 0xa91
	s_ashr_i32 s1, s0, 31
	s_lshr_b32 s1, s1, 29
	s_add_i32 s1, s0, s1
	s_ashr_i32 s2, s1, 3
	s_and_b32 s1, s1, -8
	s_sub_i32 s0, s0, s1
	s_mul_i32 s1, s0, 0x152
	s_lshr_b32 s6, s4, 6
	v_writelane_b32 v250, s5, 7
	s_add_i32 s1, s1, 2
	s_lshr_b32 s5, s4, 8
	s_lshl_b32 s31, s6, 10
	s_cmp_lt_i32 s0, 2
	s_mulk_i32 s0, 0x153
	s_cselect_b32 s0, s0, s1
	s_add_i32 s0, s0, s2
	s_mul_hi_i32 s1, s0, 0x63e7063f
	s_lshr_b32 s2, s1, 31
	s_ashr_i32 s1, s1, 7
	s_add_i32 s1, s1, s2
	s_lshl_b32 s3, s1, 3
	s_sub_i32 s2, 0x42, s3
	s_min_u32 s7, s2, 8
	s_mulk_i32 s1, 0x148
	v_lshl_or_b32 v150, v5, 12, v3
	s_sub_i32 s8, s0, s1
	v_cvt_f32_ubyte0_e32 v5, s7
	v_lshl_or_b32 v146, v6, 12, v3
	v_cvt_f32_i32_e32 v4, s8
	v_rcp_iflag_f32_e32 v6, v5
	v_lshl_or_b32 v152, v2, 12, v3
	s_ashr_i32 s0, s8, 30
	s_or_b32 s2, s0, 1
	v_mul_f32_e32 v2, v4, v6
	v_trunc_f32_e32 v2, v2
	v_fma_f32 v3, -v2, v5, v4
	v_cvt_i32_f32_e32 v2, v2
	v_cmp_ge_f32_e64 s[0:1], |v3|, v5
	s_and_b64 s[0:1], s[0:1], exec
	s_cselect_b32 s0, s2, 0
	v_readfirstlane_b32 s1, v2
	s_add_i32 s2, s1, s0
	s_mul_i32 s0, s2, s7
	s_sub_i32 s0, s8, s0
	s_sext_i32_i16 s0, s0
	s_add_i32 s12, s3, s0
	v_writelane_b32 v250, s13, 9
	s_ashr_i32 s13, s12, 31
	s_bfe_i64 s[8:9], s[2:3], 0x100000
	s_lshl_b64 s[0:1], s[12:13], 20
	s_lshl_b64 s[8:9], s[8:9], 20
	s_add_u32 s8, s84, s8
	s_addc_u32 s9, s85, s9
	s_add_i32 s13, s31, 0
	s_add_i32 m0, s13, 0x10000
	v_mov_b32_e32 v155, 0
	global_load_lds_dwordx4 v148, s[8:9]
	s_add_i32 m0, s13, 0x12000
	s_add_u32 s10, s8, 0x80000
	global_load_lds_dwordx4 v152, s[8:9]
	s_addc_u32 s11, s9, 0
	s_add_i32 m0, s13, 0x14000
	v_mov_b32_e32 v149, v155
	global_load_lds_dwordx4 v148, s[10:11]
	s_add_i32 m0, s13, 0x16000
	v_mov_b32_e32 v153, v155
	global_load_lds_dwordx4 v152, s[10:11]
	v_readlane_b32 s10, v251, 22
	v_readlane_b32 s11, v251, 23
	s_add_u32 s0, s10, s0
	s_addc_u32 s1, s11, s1
	s_add_i32 s33, s13, 0x2000
	s_mov_b32 m0, s13
	s_add_u32 s10, s0, 0x80000
	global_load_lds_dwordx4 v146, s[0:1]
	s_mov_b32 m0, s33
	s_addc_u32 s11, s1, 0
	s_add_i32 s35, s13, 0x4000
	global_load_lds_dwordx4 v150, s[0:1]
	s_mov_b32 m0, s35
	s_add_i32 s57, s13, 0x6000
	global_load_lds_dwordx4 v146, s[10:11]
	s_mov_b32 m0, s57
	s_cmp_eq_u32 s5, 1
	global_load_lds_dwordx4 v150, s[10:11]
	v_mov_b32_e32 v147, v155
	v_mov_b32_e32 v151, v155
	s_cselect_b64 s[10:11], -1, 0
	s_mov_b32 s62, 0
	v_lshl_add_u64 v[8:9], s[8:9], 0, v[148:149]
	v_lshl_add_u64 v[6:7], s[8:9], 0, v[152:153]
	v_lshl_add_u64 v[2:3], s[0:1], 0, v[146:147]
	v_writelane_b32 v250, s10, 10
	s_cmp_lg_u32 s5, 1
	v_lshl_add_u64 v[4:5], s[0:1], 0, v[150:151]
	v_writelane_b32 v250, s11, 11
	s_cbranch_scc1 .LBB0_96
	s_barrier
